# v021 + phase-18 epilogue rope-table loads software-pipelined one iteration ahead (counted waits)
# speedup vs baseline: 1.0284x; 1.0051x over previous
; __device__ __forceinline__ u32x4 pack8(const f32x4 a, const f32x4 b) { u32x4 w; w.x = cvt_pk_bf16(a[0], a[1]); w.y = cvt_pk_bf16(a[2], a[3]); w.z = cvt_pk_bf16(b[0], b[1]); w.w = cvt_pk_bf16(b[2], b[3]); return w; }
; __device__ __forceinline__ void rope8(const float* tab64, int row, int fq, const f32x4 x1a, const f32x4 x2a, const f32x4 x1b, const f32x4 x2b, f32x4& a1, f32x4& a2, f32x4& b1, f32x4& b2) {
;     const float* tp = tab64 + ((size_t)pos_index_(row) * 32 + 8 * fq) * 2;
;     const f32x4 c0 = *(const f32x4*)tp, c1 = *(const f32x4*)(tp + 4), c2 = *(const f32x4*)(tp + 8), c3 = *(const f32x4*)(tp + 12);
;     rope4(x1a, x2a, c0, c1, a1, a2); rope4(x1b, x2b, c2, c3, b1, b2);
;     __device__ __forceinline__ void operator()(const f32x4 (&acc)[2][2][4][2], const Unit& u, int wr, int wc, int fr, int fq) const {
;     ...
;             for (int m = 0; m < 4; ++m) {
;                 const int rowb = u.pm * BM + ai * HALF + wr * 64 + m * 16, row0 = rowb + (fr & 7); const size_t ro0 = (size_t)row0 * 2048;
;                 float* f0 = row0 < 8192 ? (type == 1 ? okp : ovp) + ro0 : (type == 1 ? oks : ovs) + (ro0 - (size_t)8192 * 2048);
;                 if (type < 2) {
;                     f32x4 a1, a2, b1, b2; rope8(tab64, rowb + fr, fq, acc[ai][0][m][0], acc[ai][1][m][0], acc[ai][0][m][1], acc[ai][1][m][1], a1, a2, b1, b2);
;                     if (type == 0) { a1 = a1 * qscale; a2 = a2 * qscale; b1 = b1 * qscale; b2 = b2 * qscale; }
;                     st2_bf16((type == 0 ? QA : KA) + ro0 + cw + (lo ? 0 : 32), 8 * 2048, pack8(a1, b1), pack8(a2, b2), lo, dry);
;                     if (type == 1) { st2_f32<true>(f0 + cw + (lo ? 0 : 4), 8 * 2048, a1, b1, lo, dry); st2_f32<true>(f0 + cw + 32 + (lo ? 0 : 4), 8 * 2048, a2, b2, lo, dry); }
.LBB0_3100:
	v_cndmask_b32_e64 v130, 0, 1, s[6:7]
	s_andn2_b64 vcc, exec, s[10:11]
	v_lshlrev_b32_e32 v168, 2, v139
	v_cmp_ne_u32_e64 s[6:7], 1, v130
	s_cbranch_vccnz .LBB0_3105
	v_or_b32_e32 v130, s29, v1
	v_bitop3_b32 v131, s29, v160, v1 bitop3:0xc8
	v_cmp_gt_i32_e32 vcc, s47, v130
	v_readlane_b32 s10, v254, 22
	v_readlane_b32 s11, v254, 23
	v_cndmask_b32_e32 v130, v154, v131, vcc
	v_lshl_or_b32 v130, v130, 8, v168
	s_nop 2
	global_load_dwordx4 v[170:173], v130, s[10:11]
	global_load_dwordx4 v[174:177], v130, s[10:11] offset:16
	global_load_dwordx4 v[178:181], v130, s[10:11] offset:32
	global_load_dwordx4 v[182:185], v130, s[10:11] offset:48
	v_readlane_b32 s100, v254, 22
	v_readlane_b32 s101, v254, 23
	s_add_i32 s98, s31, s66
	v_or_b32_e32 v252, s98, v1
	v_bitop3_b32 v253, s98, v161, v1 bitop3:0xc8
	v_and_or_b32 v236, v252, 31, v162
	v_cmp_gt_i32_e32 vcc, s47, v252
	v_cndmask_b32_e32 v252, v236, v253, vcc
	v_lshl_or_b32 v252, v252, 8, v168
	s_nop 2
	global_load_dwordx4 v[236:239], v252, s[100:101]
	global_load_dwordx4 v[240:243], v252, s[100:101] offset:16
	global_load_dwordx4 v[244:247], v252, s[100:101] offset:32
	global_load_dwordx4 v[248:251], v252, s[100:101] offset:48
	s_load_dwordx4 s[72:75], s[88:89], 0xe8
	s_and_b64 vcc, exec, s[6:7]
	s_mov_b64 s[10:11], 0x1b500000
	s_waitcnt vmcnt(4)
	v_mov_b32_e32 v130, v170
	v_mul_f32_e32 v170, v128, v174
	v_mul_f32_e32 v186, v120, v175
	v_mul_f32_e32 v174, v120, v174
	v_mul_f32_e32 v188, v128, v175
	v_mov_b32_e32 v120, v129
	v_mov_b32_e32 v128, v121
	v_mov_b32_e32 v190, v178
	v_mul_f32_e32 v178, v124, v182
	v_mul_f32_e32 v192, v116, v183
	v_mul_f32_e32 v182, v116, v182
	v_mul_f32_e32 v194, v124, v183
	v_mov_b32_e32 v116, v125
	v_mov_b32_e32 v124, v117
	v_mov_b32_e32 v131, v172
	v_mov_b32_e32 v172, v171
	v_mov_b32_e32 v191, v180
	v_mov_b32_e32 v180, v179
	v_pk_mul_f32 v[120:121], v[120:121], v[176:177]
	v_pk_mul_f32 v[128:129], v[128:129], v[176:177]
	v_pk_mul_f32 v[198:199], v[116:117], v[184:185]
	v_pk_mul_f32 v[184:185], v[124:125], v[184:185]
	v_pk_mul_f32 v[196:197], v[118:119], v[172:173]
	v_pk_mul_f32 v[172:173], v[126:127], v[172:173]
	v_pk_mul_f32 v[176:177], v[114:115], v[180:181]
	v_pk_mul_f32 v[180:181], v[122:123], v[180:181]
	v_mov_b32_e32 v171, v120
	v_mov_b32_e32 v187, v121
	v_mov_b32_e32 v175, v128
	v_mov_b32_e32 v189, v129
	v_mov_b32_e32 v179, v198
	v_mov_b32_e32 v193, v199
	v_mov_b32_e32 v183, v184
	v_mov_b32_e32 v195, v185
	v_pk_fma_f32 v[124:125], v[126:127], v[130:131], v[196:197] neg_lo:[0,0,1] neg_hi:[0,0,1]
	v_pk_fma_f32 v[116:117], v[118:119], v[130:131], v[172:173]
	v_pk_fma_f32 v[128:129], v[122:123], v[190:191], v[176:177] neg_lo:[0,0,1] neg_hi:[0,0,1]
	v_pk_fma_f32 v[120:121], v[114:115], v[190:191], v[180:181]
	v_pk_add_f32 v[126:127], v[170:171], v[186:187] neg_lo:[0,1] neg_hi:[0,1]
	v_pk_add_f32 v[118:119], v[174:175], v[188:189]
	v_pk_add_f32 v[130:131], v[178:179], v[192:193] neg_lo:[0,1] neg_hi:[0,1]
	v_pk_add_f32 v[122:123], v[182:183], v[194:195]
	s_cbranch_vccnz .LBB0_3103
	v_pk_mul_f32 v[126:127], v[126:127], s[26:27] op_sel_hi:[1,0]
	v_pk_mul_f32 v[124:125], v[124:125], s[26:27] op_sel_hi:[1,0]
	v_pk_mul_f32 v[118:119], v[118:119], s[26:27] op_sel_hi:[1,0]
	v_pk_mul_f32 v[116:117], v[116:117], s[26:27] op_sel_hi:[1,0]
	v_pk_mul_f32 v[130:131], v[130:131], s[26:27] op_sel_hi:[1,0]
	v_pk_mul_f32 v[128:129], v[128:129], s[26:27] op_sel_hi:[1,0]
	v_pk_mul_f32 v[122:123], v[122:123], s[26:27] op_sel_hi:[1,0]
	v_pk_mul_f32 v[120:121], v[120:121], s[26:27] op_sel_hi:[1,0]
	s_mov_b64 s[10:11], 0x19300000

; __device__ __forceinline__ u32x4 pack8(const f32x4 a, const f32x4 b) { u32x4 w; w.x = cvt_pk_bf16(a[0], a[1]); w.y = cvt_pk_bf16(a[2], a[3]); w.z = cvt_pk_bf16(b[0], b[1]); w.w = cvt_pk_bf16(b[2], b[3]); return w; }
; __device__ __forceinline__ void rope8(const float* tab64, int row, int fq, const f32x4 x1a, const f32x4 x2a, const f32x4 x1b, const f32x4 x2b, f32x4& a1, f32x4& a2, f32x4& b1, f32x4& b2) {
;     const float* tp = tab64 + ((size_t)pos_index_(row) * 32 + 8 * fq) * 2;
;     const f32x4 c0 = *(const f32x4*)tp, c1 = *(const f32x4*)(tp + 4), c2 = *(const f32x4*)(tp + 8), c3 = *(const f32x4*)(tp + 12);
;     rope4(x1a, x2a, c0, c1, a1, a2); rope4(x1b, x2b, c2, c3, b1, b2);
;     __device__ __forceinline__ void operator()(const f32x4 (&acc)[2][2][4][2], const Unit& u, int wr, int wc, int fr, int fq) const {
;     ...
;             for (int m = 0; m < 4; ++m) {
;                 const int rowb = u.pm * BM + ai * HALF + wr * 64 + m * 16, row0 = rowb + (fr & 7); const size_t ro0 = (size_t)row0 * 2048;
;                 float* f0 = row0 < 8192 ? (type == 1 ? okp : ovp) + ro0 : (type == 1 ? oks : ovs) + (ro0 - (size_t)8192 * 2048);
;                 if (type < 2) {
;                     f32x4 a1, a2, b1, b2; rope8(tab64, rowb + fr, fq, acc[ai][0][m][0], acc[ai][1][m][0], acc[ai][0][m][1], acc[ai][1][m][1], a1, a2, b1, b2);
;                     if (type == 0) { a1 = a1 * qscale; a2 = a2 * qscale; b1 = b1 * qscale; b2 = b2 * qscale; }
;                     st2_bf16((type == 0 ? QA : KA) + ro0 + cw + (lo ? 0 : 32), 8 * 2048, pack8(a1, b1), pack8(a2, b2), lo, dry);
;                     if (type == 1) { st2_f32<true>(f0 + cw + (lo ? 0 : 4), 8 * 2048, a1, b1, lo, dry); st2_f32<true>(f0 + cw + 32 + (lo ? 0 : 4), 8 * 2048, a2, b2, lo, dry); }
.LBB0_3115:
	s_andn2_b64 vcc, exec, s[40:41]
	s_cbranch_vccnz .LBB0_3120
	s_andn2_b64 vcc, exec, s[0:1]
	s_cbranch_vccnz .Lrope_q_p18_1
	s_waitcnt vmcnt(6)
	s_branch .Lrope_j_p18_1
.Lrope_q_p18_1:
	s_waitcnt vmcnt(2)
.Lrope_j_p18_1:
	v_mov_b64_e32 v[120:121], v[236:237]
	v_mov_b64_e32 v[122:123], v[238:239]
	v_mov_b64_e32 v[124:125], v[240:241]
	v_mov_b64_e32 v[126:127], v[242:243]
	v_mov_b64_e32 v[128:129], v[244:245]
	v_mov_b64_e32 v[130:131], v[246:247]
	v_mov_b64_e32 v[150:151], v[248:249]
	v_mov_b64_e32 v[152:153], v[250:251]
	v_readlane_b32 s100, v254, 22
	v_readlane_b32 s101, v254, 23
	s_add_i32 s98, s31, s67
	v_or_b32_e32 v252, s98, v1
	v_bitop3_b32 v253, s98, v163, v1 bitop3:0xc8
	v_and_or_b32 v236, v252, 47, v162
	v_cmp_gt_i32_e32 vcc, s47, v252
	v_cndmask_b32_e32 v252, v236, v253, vcc
	v_lshl_or_b32 v252, v252, 8, v168
	s_nop 2
	global_load_dwordx4 v[236:239], v252, s[100:101]
	global_load_dwordx4 v[240:243], v252, s[100:101] offset:16
	global_load_dwordx4 v[244:247], v252, s[100:101] offset:32
	global_load_dwordx4 v[248:251], v252, s[100:101] offset:48
	s_and_b64 vcc, exec, s[6:7]
	s_mov_b64 s[38:39], 0x1b500000
	v_mov_b32_e32 v114, v120
	v_mul_f32_e32 v120, v112, v124
	v_mul_f32_e32 v170, v104, v125
	v_mul_f32_e32 v124, v104, v124
	v_mul_f32_e32 v172, v112, v125
	v_mov_b32_e32 v104, v113
	v_mov_b32_e32 v112, v105
	v_mov_b32_e32 v174, v128
	v_mul_f32_e32 v128, v108, v150
	v_mul_f32_e32 v176, v100, v151
	v_mul_f32_e32 v150, v100, v150
	v_mul_f32_e32 v178, v108, v151
	v_mov_b32_e32 v100, v109
	v_mov_b32_e32 v108, v101
	v_mov_b32_e32 v115, v122
	v_mov_b32_e32 v122, v121
	v_mov_b32_e32 v175, v130
	v_mov_b32_e32 v130, v129
	v_pk_mul_f32 v[104:105], v[104:105], v[126:127]
	v_pk_mul_f32 v[112:113], v[112:113], v[126:127]
	v_pk_mul_f32 v[182:183], v[100:101], v[152:153]
	v_pk_mul_f32 v[152:153], v[108:109], v[152:153]
	v_pk_mul_f32 v[180:181], v[102:103], v[122:123]
	v_pk_mul_f32 v[122:123], v[110:111], v[122:123]
	v_pk_mul_f32 v[126:127], v[98:99], v[130:131]
	v_pk_mul_f32 v[130:131], v[106:107], v[130:131]
	v_mov_b32_e32 v121, v104
	v_mov_b32_e32 v171, v105
	v_mov_b32_e32 v125, v112
	v_mov_b32_e32 v173, v113
	v_mov_b32_e32 v129, v182
	v_mov_b32_e32 v177, v183
	v_mov_b32_e32 v151, v152
	v_mov_b32_e32 v179, v153
	v_pk_fma_f32 v[108:109], v[110:111], v[114:115], v[180:181] neg_lo:[0,0,1] neg_hi:[0,0,1]
	v_pk_fma_f32 v[100:101], v[102:103], v[114:115], v[122:123]
	v_pk_fma_f32 v[112:113], v[106:107], v[174:175], v[126:127] neg_lo:[0,0,1] neg_hi:[0,0,1]
	v_pk_fma_f32 v[104:105], v[98:99], v[174:175], v[130:131]
	v_pk_add_f32 v[110:111], v[120:121], v[170:171] neg_lo:[0,1] neg_hi:[0,1]
	v_pk_add_f32 v[102:103], v[124:125], v[172:173]
	v_pk_add_f32 v[114:115], v[128:129], v[176:177] neg_lo:[0,1] neg_hi:[0,1]
	v_pk_add_f32 v[106:107], v[150:151], v[178:179]
	s_cbranch_vccnz .LBB0_3118
	v_pk_mul_f32 v[110:111], v[110:111], s[26:27] op_sel_hi:[1,0]
	v_pk_mul_f32 v[108:109], v[108:109], s[26:27] op_sel_hi:[1,0]
	v_pk_mul_f32 v[102:103], v[102:103], s[26:27] op_sel_hi:[1,0]
	v_pk_mul_f32 v[100:101], v[100:101], s[26:27] op_sel_hi:[1,0]
	v_pk_mul_f32 v[114:115], v[114:115], s[26:27] op_sel_hi:[1,0]
	v_pk_mul_f32 v[112:113], v[112:113], s[26:27] op_sel_hi:[1,0]
	v_pk_mul_f32 v[106:107], v[106:107], s[26:27] op_sel_hi:[1,0]
	v_pk_mul_f32 v[104:105], v[104:105], s[26:27] op_sel_hi:[1,0]
	s_mov_b64 s[38:39], 0x19300000

; __device__ __forceinline__ u32x4 pack8(const f32x4 a, const f32x4 b) { u32x4 w; w.x = cvt_pk_bf16(a[0], a[1]); w.y = cvt_pk_bf16(a[2], a[3]); w.z = cvt_pk_bf16(b[0], b[1]); w.w = cvt_pk_bf16(b[2], b[3]); return w; }
; __device__ __forceinline__ void rope8(const float* tab64, int row, int fq, const f32x4 x1a, const f32x4 x2a, const f32x4 x1b, const f32x4 x2b, f32x4& a1, f32x4& a2, f32x4& b1, f32x4& b2) {
;     const float* tp = tab64 + ((size_t)pos_index_(row) * 32 + 8 * fq) * 2;
;     const f32x4 c0 = *(const f32x4*)tp, c1 = *(const f32x4*)(tp + 4), c2 = *(const f32x4*)(tp + 8), c3 = *(const f32x4*)(tp + 12);
;     rope4(x1a, x2a, c0, c1, a1, a2); rope4(x1b, x2b, c2, c3, b1, b2);
;     __device__ __forceinline__ void operator()(const f32x4 (&acc)[2][2][4][2], const Unit& u, int wr, int wc, int fr, int fq) const {
;     ...
;             for (int m = 0; m < 4; ++m) {
;                 const int rowb = u.pm * BM + ai * HALF + wr * 64 + m * 16, row0 = rowb + (fr & 7); const size_t ro0 = (size_t)row0 * 2048;
;                 float* f0 = row0 < 8192 ? (type == 1 ? okp : ovp) + ro0 : (type == 1 ? oks : ovs) + (ro0 - (size_t)8192 * 2048);
;                 if (type < 2) {
;                     f32x4 a1, a2, b1, b2; rope8(tab64, rowb + fr, fq, acc[ai][0][m][0], acc[ai][1][m][0], acc[ai][0][m][1], acc[ai][1][m][1], a1, a2, b1, b2);
;                     if (type == 0) { a1 = a1 * qscale; a2 = a2 * qscale; b1 = b1 * qscale; b2 = b2 * qscale; }
;                     st2_bf16((type == 0 ? QA : KA) + ro0 + cw + (lo ? 0 : 32), 8 * 2048, pack8(a1, b1), pack8(a2, b2), lo, dry);
;                     if (type == 1) { st2_f32<true>(f0 + cw + (lo ? 0 : 4), 8 * 2048, a1, b1, lo, dry); st2_f32<true>(f0 + cw + 32 + (lo ? 0 : 4), 8 * 2048, a2, b2, lo, dry); }
.LBB0_3131:
	s_andn2_b64 vcc, exec, s[0:1]
	s_cbranch_vccnz .Lrope_q_p18_2
	s_waitcnt vmcnt(6)
	s_branch .Lrope_j_p18_2

; __device__ __forceinline__ u32x4 pack8(const f32x4 a, const f32x4 b) { u32x4 w; w.x = cvt_pk_bf16(a[0], a[1]); w.y = cvt_pk_bf16(a[2], a[3]); w.z = cvt_pk_bf16(b[0], b[1]); w.w = cvt_pk_bf16(b[2], b[3]); return w; }
; __device__ __forceinline__ void rope8(const float* tab64, int row, int fq, const f32x4 x1a, const f32x4 x2a, const f32x4 x1b, const f32x4 x2b, f32x4& a1, f32x4& a2, f32x4& b1, f32x4& b2) {
;     const float* tp = tab64 + ((size_t)pos_index_(row) * 32 + 8 * fq) * 2;
;     const f32x4 c0 = *(const f32x4*)tp, c1 = *(const f32x4*)(tp + 4), c2 = *(const f32x4*)(tp + 8), c3 = *(const f32x4*)(tp + 12);
;     rope4(x1a, x2a, c0, c1, a1, a2); rope4(x1b, x2b, c2, c3, b1, b2);
;     __device__ __forceinline__ void operator()(const f32x4 (&acc)[2][2][4][2], const Unit& u, int wr, int wc, int fr, int fq) const {
;     ...
;             for (int m = 0; m < 4; ++m) {
;                 const int rowb = u.pm * BM + ai * HALF + wr * 64 + m * 16, row0 = rowb + (fr & 7); const size_t ro0 = (size_t)row0 * 2048;
;                 float* f0 = row0 < 8192 ? (type == 1 ? okp : ovp) + ro0 : (type == 1 ? oks : ovs) + (ro0 - (size_t)8192 * 2048);
;                 if (type < 2) {
;                     f32x4 a1, a2, b1, b2; rope8(tab64, rowb + fr, fq, acc[ai][0][m][0], acc[ai][1][m][0], acc[ai][0][m][1], acc[ai][1][m][1], a1, a2, b1, b2);
;                     if (type == 0) { a1 = a1 * qscale; a2 = a2 * qscale; b1 = b1 * qscale; b2 = b2 * qscale; }
;                     st2_bf16((type == 0 ? QA : KA) + ro0 + cw + (lo ? 0 : 32), 8 * 2048, pack8(a1, b1), pack8(a2, b2), lo, dry);
;                     if (type == 1) { st2_f32<true>(f0 + cw + (lo ? 0 : 4), 8 * 2048, a1, b1, lo, dry); st2_f32<true>(f0 + cw + 32 + (lo ? 0 : 4), 8 * 2048, a2, b2, lo, dry); }
.Lrope_j_p18_2:
	v_mov_b64_e32 v[104:105], v[236:237]
	v_mov_b64_e32 v[106:107], v[238:239]
	v_mov_b64_e32 v[108:109], v[240:241]
	v_mov_b64_e32 v[110:111], v[242:243]
	v_mov_b64_e32 v[112:113], v[244:245]
	v_mov_b64_e32 v[114:115], v[246:247]
	v_mov_b64_e32 v[116:117], v[248:249]
	v_mov_b64_e32 v[118:119], v[250:251]
	v_readlane_b32 s100, v254, 22
	v_readlane_b32 s101, v254, 23
	s_add_i32 s98, s31, s68
	v_or_b32_e32 v252, s98, v1
	v_bitop3_b32 v253, s98, v166, v1 bitop3:0xc8
	v_and_or_b32 v236, v252, 63, v162
	v_cmp_gt_i32_e32 vcc, s47, v252
	v_cndmask_b32_e32 v252, v236, v253, vcc
	v_lshl_or_b32 v252, v252, 8, v168
	s_nop 2
	global_load_dwordx4 v[236:239], v252, s[100:101]
	global_load_dwordx4 v[240:243], v252, s[100:101] offset:16
	global_load_dwordx4 v[244:247], v252, s[100:101] offset:32
	global_load_dwordx4 v[248:251], v252, s[100:101] offset:48
	s_and_b64 vcc, exec, s[6:7]
	s_mov_b64 s[38:39], 0x1b500000
	v_mov_b32_e32 v98, v104
	v_mul_f32_e32 v104, v96, v108
	v_mul_f32_e32 v120, v88, v109
	v_mul_f32_e32 v108, v88, v108
	v_mul_f32_e32 v122, v96, v109
	v_mov_b32_e32 v88, v97
	v_mov_b32_e32 v96, v89
	v_mov_b32_e32 v124, v112
	v_mul_f32_e32 v112, v92, v116
	v_mul_f32_e32 v126, v84, v117
	v_mul_f32_e32 v116, v84, v116
	v_mul_f32_e32 v128, v92, v117
	v_mov_b32_e32 v84, v93
	v_mov_b32_e32 v92, v85
	v_mov_b32_e32 v99, v106
	v_mov_b32_e32 v106, v105
	v_mov_b32_e32 v125, v114
	v_mov_b32_e32 v114, v113
	v_pk_mul_f32 v[88:89], v[88:89], v[110:111]
	v_pk_mul_f32 v[96:97], v[96:97], v[110:111]
	v_pk_mul_f32 v[150:151], v[84:85], v[118:119]
	v_pk_mul_f32 v[118:119], v[92:93], v[118:119]
	v_pk_mul_f32 v[130:131], v[86:87], v[106:107]
	v_pk_mul_f32 v[106:107], v[94:95], v[106:107]
	v_pk_mul_f32 v[110:111], v[82:83], v[114:115]
	v_pk_mul_f32 v[114:115], v[90:91], v[114:115]
	v_mov_b32_e32 v105, v88
	v_mov_b32_e32 v121, v89
	v_mov_b32_e32 v109, v96
	v_mov_b32_e32 v123, v97
	v_mov_b32_e32 v113, v150
	v_mov_b32_e32 v127, v151
	v_mov_b32_e32 v117, v118
	v_mov_b32_e32 v129, v119
	v_pk_fma_f32 v[92:93], v[94:95], v[98:99], v[130:131] neg_lo:[0,0,1] neg_hi:[0,0,1]
	v_pk_fma_f32 v[84:85], v[86:87], v[98:99], v[106:107]
	v_pk_fma_f32 v[96:97], v[90:91], v[124:125], v[110:111] neg_lo:[0,0,1] neg_hi:[0,0,1]
	v_pk_fma_f32 v[88:89], v[82:83], v[124:125], v[114:115]
	v_pk_add_f32 v[94:95], v[104:105], v[120:121] neg_lo:[0,1] neg_hi:[0,1]
	v_pk_add_f32 v[86:87], v[108:109], v[122:123]
	v_pk_add_f32 v[98:99], v[112:113], v[126:127] neg_lo:[0,1] neg_hi:[0,1]
	v_pk_add_f32 v[90:91], v[116:117], v[128:129]
	s_cbranch_vccnz .LBB0_3133
	v_pk_mul_f32 v[94:95], v[94:95], s[26:27] op_sel_hi:[1,0]
	v_pk_mul_f32 v[92:93], v[92:93], s[26:27] op_sel_hi:[1,0]
	v_pk_mul_f32 v[86:87], v[86:87], s[26:27] op_sel_hi:[1,0]
	v_pk_mul_f32 v[84:85], v[84:85], s[26:27] op_sel_hi:[1,0]
	v_pk_mul_f32 v[98:99], v[98:99], s[26:27] op_sel_hi:[1,0]
	v_pk_mul_f32 v[96:97], v[96:97], s[26:27] op_sel_hi:[1,0]
	v_pk_mul_f32 v[90:91], v[90:91], s[26:27] op_sel_hi:[1,0]
	v_pk_mul_f32 v[88:89], v[88:89], s[26:27] op_sel_hi:[1,0]
	s_mov_b64 s[38:39], 0x19300000

; __device__ __forceinline__ u32x4 pack8(const f32x4 a, const f32x4 b) { u32x4 w; w.x = cvt_pk_bf16(a[0], a[1]); w.y = cvt_pk_bf16(a[2], a[3]); w.z = cvt_pk_bf16(b[0], b[1]); w.w = cvt_pk_bf16(b[2], b[3]); return w; }
; __device__ __forceinline__ void rope8(const float* tab64, int row, int fq, const f32x4 x1a, const f32x4 x2a, const f32x4 x1b, const f32x4 x2b, f32x4& a1, f32x4& a2, f32x4& b1, f32x4& b2) {
;     const float* tp = tab64 + ((size_t)pos_index_(row) * 32 + 8 * fq) * 2;
;     const f32x4 c0 = *(const f32x4*)tp, c1 = *(const f32x4*)(tp + 4), c2 = *(const f32x4*)(tp + 8), c3 = *(const f32x4*)(tp + 12);
;     rope4(x1a, x2a, c0, c1, a1, a2); rope4(x1b, x2b, c2, c3, b1, b2);
;     __device__ __forceinline__ void operator()(const f32x4 (&acc)[2][2][4][2], const Unit& u, int wr, int wc, int fr, int fq) const {
;     ...
;             for (int m = 0; m < 4; ++m) {
;                 const int rowb = u.pm * BM + ai * HALF + wr * 64 + m * 16, row0 = rowb + (fr & 7); const size_t ro0 = (size_t)row0 * 2048;
;                 float* f0 = row0 < 8192 ? (type == 1 ? okp : ovp) + ro0 : (type == 1 ? oks : ovs) + (ro0 - (size_t)8192 * 2048);
;                 if (type < 2) {
;                     f32x4 a1, a2, b1, b2; rope8(tab64, rowb + fr, fq, acc[ai][0][m][0], acc[ai][1][m][0], acc[ai][0][m][1], acc[ai][1][m][1], a1, a2, b1, b2);
;                     if (type == 0) { a1 = a1 * qscale; a2 = a2 * qscale; b1 = b1 * qscale; b2 = b2 * qscale; }
;                     st2_bf16((type == 0 ? QA : KA) + ro0 + cw + (lo ? 0 : 32), 8 * 2048, pack8(a1, b1), pack8(a2, b2), lo, dry);
;                     if (type == 1) { st2_f32<true>(f0 + cw + (lo ? 0 : 4), 8 * 2048, a1, b1, lo, dry); st2_f32<true>(f0 + cw + 32 + (lo ? 0 : 4), 8 * 2048, a2, b2, lo, dry); }
.Lrope_j_p18_3:
	v_mov_b64_e32 v[88:89], v[236:237]
	v_mov_b64_e32 v[90:91], v[238:239]
	v_mov_b64_e32 v[92:93], v[240:241]
	v_mov_b64_e32 v[94:95], v[242:243]
	v_mov_b64_e32 v[96:97], v[244:245]
	v_mov_b64_e32 v[98:99], v[246:247]
	v_mov_b64_e32 v[100:101], v[248:249]
	v_mov_b64_e32 v[102:103], v[250:251]
	v_readlane_b32 s100, v254, 22
	v_readlane_b32 s101, v254, 23
	s_add_i32 s98, s29, 0x80
	v_or_b32_e32 v252, s98, v1
	v_bitop3_b32 v253, s98, v160, v1 bitop3:0xc8
	v_cmp_gt_i32_e32 vcc, s47, v252
	v_cndmask_b32_e32 v252, v154, v253, vcc
	v_lshl_or_b32 v252, v252, 8, v168
	s_nop 2
	global_load_dwordx4 v[236:239], v252, s[100:101]
	global_load_dwordx4 v[240:243], v252, s[100:101] offset:16
	global_load_dwordx4 v[244:247], v252, s[100:101] offset:32
	global_load_dwordx4 v[248:251], v252, s[100:101] offset:48
	s_and_b64 vcc, exec, s[6:7]
	s_mov_b64 s[38:39], 0x1b500000
	v_mov_b32_e32 v82, v88
	v_mul_f32_e32 v88, v80, v92
	v_mul_f32_e32 v104, v72, v93
	v_mul_f32_e32 v92, v72, v92
	v_mul_f32_e32 v106, v80, v93
	v_mov_b32_e32 v72, v81
	v_mov_b32_e32 v80, v73
	v_mov_b32_e32 v108, v96
	v_mul_f32_e32 v96, v76, v100
	v_mul_f32_e32 v110, v68, v101
	v_mul_f32_e32 v100, v68, v100
	v_mul_f32_e32 v112, v76, v101
	v_mov_b32_e32 v68, v77
	v_mov_b32_e32 v76, v69
	v_mov_b32_e32 v83, v90
	v_mov_b32_e32 v90, v89
	v_mov_b32_e32 v109, v98
	v_mov_b32_e32 v98, v97
	v_pk_mul_f32 v[72:73], v[72:73], v[94:95]
	v_pk_mul_f32 v[80:81], v[80:81], v[94:95]
	v_pk_mul_f32 v[116:117], v[68:69], v[102:103]
	v_pk_mul_f32 v[102:103], v[76:77], v[102:103]
	v_pk_mul_f32 v[114:115], v[70:71], v[90:91]
	v_pk_mul_f32 v[90:91], v[78:79], v[90:91]
	v_pk_mul_f32 v[94:95], v[66:67], v[98:99]
	v_pk_mul_f32 v[98:99], v[74:75], v[98:99]
	v_mov_b32_e32 v89, v72
	v_mov_b32_e32 v105, v73
	v_mov_b32_e32 v93, v80
	v_mov_b32_e32 v107, v81
	v_mov_b32_e32 v97, v116
	v_mov_b32_e32 v111, v117
	v_mov_b32_e32 v101, v102
	v_mov_b32_e32 v113, v103
	v_pk_fma_f32 v[76:77], v[78:79], v[82:83], v[114:115] neg_lo:[0,0,1] neg_hi:[0,0,1]
	v_pk_fma_f32 v[68:69], v[70:71], v[82:83], v[90:91]
	v_pk_fma_f32 v[80:81], v[74:75], v[108:109], v[94:95] neg_lo:[0,0,1] neg_hi:[0,0,1]
	v_pk_fma_f32 v[72:73], v[66:67], v[108:109], v[98:99]
	v_pk_add_f32 v[78:79], v[88:89], v[104:105] neg_lo:[0,1] neg_hi:[0,1]
	v_pk_add_f32 v[70:71], v[92:93], v[106:107]
	v_pk_add_f32 v[82:83], v[96:97], v[110:111] neg_lo:[0,1] neg_hi:[0,1]
	v_pk_add_f32 v[74:75], v[100:101], v[112:113]
	s_cbranch_vccnz .LBB0_3148
	v_pk_mul_f32 v[78:79], v[78:79], s[26:27] op_sel_hi:[1,0]
	v_pk_mul_f32 v[76:77], v[76:77], s[26:27] op_sel_hi:[1,0]
	v_pk_mul_f32 v[70:71], v[70:71], s[26:27] op_sel_hi:[1,0]
	v_pk_mul_f32 v[68:69], v[68:69], s[26:27] op_sel_hi:[1,0]
	v_pk_mul_f32 v[82:83], v[82:83], s[26:27] op_sel_hi:[1,0]
	v_pk_mul_f32 v[80:81], v[80:81], s[26:27] op_sel_hi:[1,0]
	v_pk_mul_f32 v[74:75], v[74:75], s[26:27] op_sel_hi:[1,0]
	v_pk_mul_f32 v[72:73], v[72:73], s[26:27] op_sel_hi:[1,0]
	s_mov_b64 s[38:39], 0x19300000

; __device__ __forceinline__ u32x4 pack8(const f32x4 a, const f32x4 b) { u32x4 w; w.x = cvt_pk_bf16(a[0], a[1]); w.y = cvt_pk_bf16(a[2], a[3]); w.z = cvt_pk_bf16(b[0], b[1]); w.w = cvt_pk_bf16(b[2], b[3]); return w; }
; __device__ __forceinline__ void rope8(const float* tab64, int row, int fq, const f32x4 x1a, const f32x4 x2a, const f32x4 x1b, const f32x4 x2b, f32x4& a1, f32x4& a2, f32x4& b1, f32x4& b2) {
;     const float* tp = tab64 + ((size_t)pos_index_(row) * 32 + 8 * fq) * 2;
;     const f32x4 c0 = *(const f32x4*)tp, c1 = *(const f32x4*)(tp + 4), c2 = *(const f32x4*)(tp + 8), c3 = *(const f32x4*)(tp + 12);
;     rope4(x1a, x2a, c0, c1, a1, a2); rope4(x1b, x2b, c2, c3, b1, b2);
;     __device__ __forceinline__ void operator()(const f32x4 (&acc)[2][2][4][2], const Unit& u, int wr, int wc, int fr, int fq) const {
;     ...
;             for (int m = 0; m < 4; ++m) {
;                 const int rowb = u.pm * BM + ai * HALF + wr * 64 + m * 16, row0 = rowb + (fr & 7); const size_t ro0 = (size_t)row0 * 2048;
;                 float* f0 = row0 < 8192 ? (type == 1 ? okp : ovp) + ro0 : (type == 1 ? oks : ovs) + (ro0 - (size_t)8192 * 2048);
;                 if (type < 2) {
;                     f32x4 a1, a2, b1, b2; rope8(tab64, rowb + fr, fq, acc[ai][0][m][0], acc[ai][1][m][0], acc[ai][0][m][1], acc[ai][1][m][1], a1, a2, b1, b2);
;                     if (type == 0) { a1 = a1 * qscale; a2 = a2 * qscale; b1 = b1 * qscale; b2 = b2 * qscale; }
;                     st2_bf16((type == 0 ? QA : KA) + ro0 + cw + (lo ? 0 : 32), 8 * 2048, pack8(a1, b1), pack8(a2, b2), lo, dry);
;                     if (type == 1) { st2_f32<true>(f0 + cw + (lo ? 0 : 4), 8 * 2048, a1, b1, lo, dry); st2_f32<true>(f0 + cw + 32 + (lo ? 0 : 4), 8 * 2048, a2, b2, lo, dry); }
.Lrope_j_p18_4:
	v_mov_b64_e32 v[72:73], v[236:237]
	v_mov_b64_e32 v[74:75], v[238:239]
	v_mov_b64_e32 v[76:77], v[240:241]
	v_mov_b64_e32 v[78:79], v[242:243]
	v_mov_b64_e32 v[80:81], v[244:245]
	v_mov_b64_e32 v[82:83], v[246:247]
	v_mov_b64_e32 v[84:85], v[248:249]
	v_mov_b64_e32 v[86:87], v[250:251]
	v_readlane_b32 s100, v254, 22
	v_readlane_b32 s101, v254, 23
	s_add_i32 s98, s29, 0x90
	v_or_b32_e32 v252, s98, v1
	v_bitop3_b32 v253, s98, v161, v1 bitop3:0xc8
	v_and_or_b32 v236, v252, 31, v162
	v_cmp_gt_i32_e32 vcc, s47, v252
	v_cndmask_b32_e32 v252, v236, v253, vcc
	v_lshl_or_b32 v252, v252, 8, v168
	s_nop 2
	global_load_dwordx4 v[236:239], v252, s[100:101]
	global_load_dwordx4 v[240:243], v252, s[100:101] offset:16
	global_load_dwordx4 v[244:247], v252, s[100:101] offset:32
	global_load_dwordx4 v[248:251], v252, s[100:101] offset:48
	s_and_b64 vcc, exec, s[6:7]
	s_mov_b64 s[38:39], 0x1b500000
	v_mov_b32_e32 v66, v72
	v_mul_f32_e32 v72, v64, v76
	v_mul_f32_e32 v88, v56, v77
	v_mul_f32_e32 v76, v56, v76
	v_mul_f32_e32 v90, v64, v77
	v_mov_b32_e32 v56, v65
	v_mov_b32_e32 v64, v57
	v_mov_b32_e32 v92, v80
	v_mul_f32_e32 v80, v60, v84
	v_mul_f32_e32 v94, v52, v85
	v_mul_f32_e32 v84, v52, v84
	v_mul_f32_e32 v96, v60, v85
	v_mov_b32_e32 v52, v61
	v_mov_b32_e32 v60, v53
	v_mov_b32_e32 v67, v74
	v_mov_b32_e32 v74, v73
	v_mov_b32_e32 v93, v82
	v_mov_b32_e32 v82, v81
	v_pk_mul_f32 v[56:57], v[56:57], v[78:79]
	v_pk_mul_f32 v[64:65], v[64:65], v[78:79]
	v_pk_mul_f32 v[100:101], v[52:53], v[86:87]
	v_pk_mul_f32 v[86:87], v[60:61], v[86:87]
	v_pk_mul_f32 v[98:99], v[54:55], v[74:75]
	v_pk_mul_f32 v[74:75], v[62:63], v[74:75]
	v_pk_mul_f32 v[78:79], v[50:51], v[82:83]
	v_pk_mul_f32 v[82:83], v[58:59], v[82:83]
	v_mov_b32_e32 v73, v56
	v_mov_b32_e32 v89, v57
	v_mov_b32_e32 v77, v64
	v_mov_b32_e32 v91, v65
	v_mov_b32_e32 v81, v100
	v_mov_b32_e32 v95, v101
	v_mov_b32_e32 v85, v86
	v_mov_b32_e32 v97, v87
	v_pk_fma_f32 v[60:61], v[62:63], v[66:67], v[98:99] neg_lo:[0,0,1] neg_hi:[0,0,1]
	v_pk_fma_f32 v[52:53], v[54:55], v[66:67], v[74:75]
	v_pk_fma_f32 v[64:65], v[58:59], v[92:93], v[78:79] neg_lo:[0,0,1] neg_hi:[0,0,1]
	v_pk_fma_f32 v[56:57], v[50:51], v[92:93], v[82:83]
	v_pk_add_f32 v[62:63], v[72:73], v[88:89] neg_lo:[0,1] neg_hi:[0,1]
	v_pk_add_f32 v[54:55], v[76:77], v[90:91]
	v_pk_add_f32 v[66:67], v[80:81], v[94:95] neg_lo:[0,1] neg_hi:[0,1]
	v_pk_add_f32 v[58:59], v[84:85], v[96:97]
	s_cbranch_vccnz .LBB0_3163
	v_pk_mul_f32 v[62:63], v[62:63], s[26:27] op_sel_hi:[1,0]
	v_pk_mul_f32 v[60:61], v[60:61], s[26:27] op_sel_hi:[1,0]
	v_pk_mul_f32 v[54:55], v[54:55], s[26:27] op_sel_hi:[1,0]
	v_pk_mul_f32 v[52:53], v[52:53], s[26:27] op_sel_hi:[1,0]
	v_pk_mul_f32 v[66:67], v[66:67], s[26:27] op_sel_hi:[1,0]
	v_pk_mul_f32 v[64:65], v[64:65], s[26:27] op_sel_hi:[1,0]
	v_pk_mul_f32 v[58:59], v[58:59], s[26:27] op_sel_hi:[1,0]
	v_pk_mul_f32 v[56:57], v[56:57], s[26:27] op_sel_hi:[1,0]
	s_mov_b64 s[38:39], 0x19300000

; __device__ __forceinline__ u32x4 pack8(const f32x4 a, const f32x4 b) { u32x4 w; w.x = cvt_pk_bf16(a[0], a[1]); w.y = cvt_pk_bf16(a[2], a[3]); w.z = cvt_pk_bf16(b[0], b[1]); w.w = cvt_pk_bf16(b[2], b[3]); return w; }
; __device__ __forceinline__ void rope8(const float* tab64, int row, int fq, const f32x4 x1a, const f32x4 x2a, const f32x4 x1b, const f32x4 x2b, f32x4& a1, f32x4& a2, f32x4& b1, f32x4& b2) {
;     const float* tp = tab64 + ((size_t)pos_index_(row) * 32 + 8 * fq) * 2;
;     const f32x4 c0 = *(const f32x4*)tp, c1 = *(const f32x4*)(tp + 4), c2 = *(const f32x4*)(tp + 8), c3 = *(const f32x4*)(tp + 12);
;     rope4(x1a, x2a, c0, c1, a1, a2); rope4(x1b, x2b, c2, c3, b1, b2);
;     __device__ __forceinline__ void operator()(const f32x4 (&acc)[2][2][4][2], const Unit& u, int wr, int wc, int fr, int fq) const {
;     ...
;             for (int m = 0; m < 4; ++m) {
;                 const int rowb = u.pm * BM + ai * HALF + wr * 64 + m * 16, row0 = rowb + (fr & 7); const size_t ro0 = (size_t)row0 * 2048;
;                 float* f0 = row0 < 8192 ? (type == 1 ? okp : ovp) + ro0 : (type == 1 ? oks : ovs) + (ro0 - (size_t)8192 * 2048);
;                 if (type < 2) {
;                     f32x4 a1, a2, b1, b2; rope8(tab64, rowb + fr, fq, acc[ai][0][m][0], acc[ai][1][m][0], acc[ai][0][m][1], acc[ai][1][m][1], a1, a2, b1, b2);
;                     if (type == 0) { a1 = a1 * qscale; a2 = a2 * qscale; b1 = b1 * qscale; b2 = b2 * qscale; }
;                     st2_bf16((type == 0 ? QA : KA) + ro0 + cw + (lo ? 0 : 32), 8 * 2048, pack8(a1, b1), pack8(a2, b2), lo, dry);
;                     if (type == 1) { st2_f32<true>(f0 + cw + (lo ? 0 : 4), 8 * 2048, a1, b1, lo, dry); st2_f32<true>(f0 + cw + 32 + (lo ? 0 : 4), 8 * 2048, a2, b2, lo, dry); }
.Lrope_j_p18_5:
	v_mov_b64_e32 v[56:57], v[236:237]
	v_mov_b64_e32 v[58:59], v[238:239]
	v_mov_b64_e32 v[60:61], v[240:241]
	v_mov_b64_e32 v[62:63], v[242:243]
	v_mov_b64_e32 v[64:65], v[244:245]
	v_mov_b64_e32 v[66:67], v[246:247]
	v_mov_b64_e32 v[68:69], v[248:249]
	v_mov_b64_e32 v[70:71], v[250:251]
	v_readlane_b32 s100, v254, 22
	v_readlane_b32 s101, v254, 23
	s_add_i32 s98, s29, 0xa0
	v_or_b32_e32 v252, s98, v1
	v_bitop3_b32 v253, s98, v163, v1 bitop3:0xc8
	v_and_or_b32 v236, v252, 47, v162
	v_cmp_gt_i32_e32 vcc, s47, v252
	v_cndmask_b32_e32 v252, v236, v253, vcc
	v_lshl_or_b32 v252, v252, 8, v168
	s_nop 2
	global_load_dwordx4 v[236:239], v252, s[100:101]
	global_load_dwordx4 v[240:243], v252, s[100:101] offset:16
	global_load_dwordx4 v[244:247], v252, s[100:101] offset:32
	global_load_dwordx4 v[248:251], v252, s[100:101] offset:48
	s_and_b64 vcc, exec, s[6:7]
	s_mov_b64 s[38:39], 0x1b500000
	v_mov_b32_e32 v50, v56
	v_mul_f32_e32 v56, v48, v60
	v_mul_f32_e32 v72, v40, v61
	v_mul_f32_e32 v60, v40, v60
	v_mul_f32_e32 v74, v48, v61
	v_mov_b32_e32 v40, v49
	v_mov_b32_e32 v48, v41
	v_mov_b32_e32 v76, v64
	v_mul_f32_e32 v64, v44, v68
	v_mul_f32_e32 v78, v36, v69
	v_mul_f32_e32 v68, v36, v68
	v_mul_f32_e32 v80, v44, v69
	v_mov_b32_e32 v36, v45
	v_mov_b32_e32 v44, v37
	v_mov_b32_e32 v51, v58
	v_mov_b32_e32 v58, v57
	v_mov_b32_e32 v77, v66
	v_mov_b32_e32 v66, v65
	v_pk_mul_f32 v[40:41], v[40:41], v[62:63]
	v_pk_mul_f32 v[48:49], v[48:49], v[62:63]
	v_pk_mul_f32 v[84:85], v[36:37], v[70:71]
	v_pk_mul_f32 v[70:71], v[44:45], v[70:71]
	v_pk_mul_f32 v[82:83], v[38:39], v[58:59]
	v_pk_mul_f32 v[58:59], v[46:47], v[58:59]
	v_pk_mul_f32 v[62:63], v[34:35], v[66:67]
	v_pk_mul_f32 v[66:67], v[42:43], v[66:67]
	v_mov_b32_e32 v57, v40
	v_mov_b32_e32 v73, v41
	v_mov_b32_e32 v61, v48
	v_mov_b32_e32 v75, v49
	v_mov_b32_e32 v65, v84
	v_mov_b32_e32 v79, v85
	v_mov_b32_e32 v69, v70
	v_mov_b32_e32 v81, v71
	v_pk_fma_f32 v[44:45], v[46:47], v[50:51], v[82:83] neg_lo:[0,0,1] neg_hi:[0,0,1]
	v_pk_fma_f32 v[36:37], v[38:39], v[50:51], v[58:59]
	v_pk_fma_f32 v[48:49], v[42:43], v[76:77], v[62:63] neg_lo:[0,0,1] neg_hi:[0,0,1]
	v_pk_fma_f32 v[40:41], v[34:35], v[76:77], v[66:67]
	v_pk_add_f32 v[46:47], v[56:57], v[72:73] neg_lo:[0,1] neg_hi:[0,1]
	v_pk_add_f32 v[38:39], v[60:61], v[74:75]
	v_pk_add_f32 v[50:51], v[64:65], v[78:79] neg_lo:[0,1] neg_hi:[0,1]
	v_pk_add_f32 v[42:43], v[68:69], v[80:81]
	s_cbranch_vccnz .LBB0_3178
	v_pk_mul_f32 v[46:47], v[46:47], s[26:27] op_sel_hi:[1,0]
	v_pk_mul_f32 v[44:45], v[44:45], s[26:27] op_sel_hi:[1,0]
	v_pk_mul_f32 v[38:39], v[38:39], s[26:27] op_sel_hi:[1,0]
	v_pk_mul_f32 v[36:37], v[36:37], s[26:27] op_sel_hi:[1,0]
	v_pk_mul_f32 v[50:51], v[50:51], s[26:27] op_sel_hi:[1,0]
	v_pk_mul_f32 v[48:49], v[48:49], s[26:27] op_sel_hi:[1,0]
	v_pk_mul_f32 v[42:43], v[42:43], s[26:27] op_sel_hi:[1,0]
	v_pk_mul_f32 v[40:41], v[40:41], s[26:27] op_sel_hi:[1,0]
	s_mov_b64 s[38:39], 0x19300000

; __device__ __forceinline__ u32x4 pack8(const f32x4 a, const f32x4 b) { u32x4 w; w.x = cvt_pk_bf16(a[0], a[1]); w.y = cvt_pk_bf16(a[2], a[3]); w.z = cvt_pk_bf16(b[0], b[1]); w.w = cvt_pk_bf16(b[2], b[3]); return w; }
; __device__ __forceinline__ void rope8(const float* tab64, int row, int fq, const f32x4 x1a, const f32x4 x2a, const f32x4 x1b, const f32x4 x2b, f32x4& a1, f32x4& a2, f32x4& b1, f32x4& b2) {
;     const float* tp = tab64 + ((size_t)pos_index_(row) * 32 + 8 * fq) * 2;
;     const f32x4 c0 = *(const f32x4*)tp, c1 = *(const f32x4*)(tp + 4), c2 = *(const f32x4*)(tp + 8), c3 = *(const f32x4*)(tp + 12);
;     rope4(x1a, x2a, c0, c1, a1, a2); rope4(x1b, x2b, c2, c3, b1, b2);
;     __device__ __forceinline__ void operator()(const f32x4 (&acc)[2][2][4][2], const Unit& u, int wr, int wc, int fr, int fq) const {
;     ...
;             for (int m = 0; m < 4; ++m) {
;                 const int rowb = u.pm * BM + ai * HALF + wr * 64 + m * 16, row0 = rowb + (fr & 7); const size_t ro0 = (size_t)row0 * 2048;
;                 float* f0 = row0 < 8192 ? (type == 1 ? okp : ovp) + ro0 : (type == 1 ? oks : ovs) + (ro0 - (size_t)8192 * 2048);
;                 if (type < 2) {
;                     f32x4 a1, a2, b1, b2; rope8(tab64, rowb + fr, fq, acc[ai][0][m][0], acc[ai][1][m][0], acc[ai][0][m][1], acc[ai][1][m][1], a1, a2, b1, b2);
;                     if (type == 0) { a1 = a1 * qscale; a2 = a2 * qscale; b1 = b1 * qscale; b2 = b2 * qscale; }
;                     st2_bf16((type == 0 ? QA : KA) + ro0 + cw + (lo ? 0 : 32), 8 * 2048, pack8(a1, b1), pack8(a2, b2), lo, dry);
;                     if (type == 1) { st2_f32<true>(f0 + cw + (lo ? 0 : 4), 8 * 2048, a1, b1, lo, dry); st2_f32<true>(f0 + cw + 32 + (lo ? 0 : 4), 8 * 2048, a2, b2, lo, dry); }
.Lrope_j_p18_6:
	v_mov_b64_e32 v[40:41], v[236:237]
	v_mov_b64_e32 v[42:43], v[238:239]
	v_mov_b64_e32 v[44:45], v[240:241]
	v_mov_b64_e32 v[46:47], v[242:243]
	v_mov_b64_e32 v[48:49], v[244:245]
	v_mov_b64_e32 v[50:51], v[246:247]
	v_mov_b64_e32 v[52:53], v[248:249]
	v_mov_b64_e32 v[54:55], v[250:251]
	v_readlane_b32 s100, v254, 22
	v_readlane_b32 s101, v254, 23
	s_add_i32 s98, s29, 0xb0
	v_or_b32_e32 v252, s98, v1
	v_bitop3_b32 v253, s98, v166, v1 bitop3:0xc8
	v_and_or_b32 v236, v252, 63, v162
	v_cmp_gt_i32_e32 vcc, s47, v252
	v_cndmask_b32_e32 v252, v236, v253, vcc
	v_lshl_or_b32 v252, v252, 8, v168
	s_nop 2
	global_load_dwordx4 v[236:239], v252, s[100:101]
	global_load_dwordx4 v[240:243], v252, s[100:101] offset:16
	global_load_dwordx4 v[244:247], v252, s[100:101] offset:32
	global_load_dwordx4 v[248:251], v252, s[100:101] offset:48
	s_and_b64 vcc, exec, s[6:7]
	s_mov_b64 s[38:39], 0x1b500000
	v_mov_b32_e32 v34, v40
	v_mul_f32_e32 v40, v32, v44
	v_mul_f32_e32 v56, v24, v45
	v_mul_f32_e32 v44, v24, v44
	v_mul_f32_e32 v58, v32, v45
	v_mov_b32_e32 v24, v33
	v_mov_b32_e32 v32, v25
	v_mov_b32_e32 v60, v48
	v_mul_f32_e32 v48, v28, v52
	v_mul_f32_e32 v62, v20, v53
	v_mul_f32_e32 v52, v20, v52
	v_mul_f32_e32 v64, v28, v53
	v_mov_b32_e32 v20, v29
	v_mov_b32_e32 v28, v21
	v_mov_b32_e32 v35, v42
	v_mov_b32_e32 v42, v41
	v_mov_b32_e32 v61, v50
	v_mov_b32_e32 v50, v49
	v_pk_mul_f32 v[24:25], v[24:25], v[46:47]
	v_pk_mul_f32 v[32:33], v[32:33], v[46:47]
	v_pk_mul_f32 v[68:69], v[20:21], v[54:55]
	v_pk_mul_f32 v[54:55], v[28:29], v[54:55]
	v_pk_mul_f32 v[66:67], v[22:23], v[42:43]
	v_pk_mul_f32 v[42:43], v[30:31], v[42:43]
	v_pk_mul_f32 v[46:47], v[18:19], v[50:51]
	v_pk_mul_f32 v[50:51], v[26:27], v[50:51]
	v_mov_b32_e32 v41, v24
	v_mov_b32_e32 v57, v25
	v_mov_b32_e32 v45, v32
	v_mov_b32_e32 v59, v33
	v_mov_b32_e32 v49, v68
	v_mov_b32_e32 v63, v69
	v_mov_b32_e32 v53, v54
	v_mov_b32_e32 v65, v55
	v_pk_fma_f32 v[28:29], v[30:31], v[34:35], v[66:67] neg_lo:[0,0,1] neg_hi:[0,0,1]
	v_pk_fma_f32 v[20:21], v[22:23], v[34:35], v[42:43]
	v_pk_fma_f32 v[32:33], v[26:27], v[60:61], v[46:47] neg_lo:[0,0,1] neg_hi:[0,0,1]
	v_pk_fma_f32 v[24:25], v[18:19], v[60:61], v[50:51]
	v_pk_add_f32 v[30:31], v[40:41], v[56:57] neg_lo:[0,1] neg_hi:[0,1]
	v_pk_add_f32 v[22:23], v[44:45], v[58:59]
	v_pk_add_f32 v[34:35], v[48:49], v[62:63] neg_lo:[0,1] neg_hi:[0,1]
	v_pk_add_f32 v[26:27], v[52:53], v[64:65]
	s_cbranch_vccnz .LBB0_3193
	v_pk_mul_f32 v[30:31], v[30:31], s[26:27] op_sel_hi:[1,0]
	v_pk_mul_f32 v[28:29], v[28:29], s[26:27] op_sel_hi:[1,0]
	v_pk_mul_f32 v[22:23], v[22:23], s[26:27] op_sel_hi:[1,0]
	v_pk_mul_f32 v[20:21], v[20:21], s[26:27] op_sel_hi:[1,0]
	v_pk_mul_f32 v[34:35], v[34:35], s[26:27] op_sel_hi:[1,0]
	v_pk_mul_f32 v[32:33], v[32:33], s[26:27] op_sel_hi:[1,0]
	v_pk_mul_f32 v[26:27], v[26:27], s[26:27] op_sel_hi:[1,0]
	v_pk_mul_f32 v[24:25], v[24:25], s[26:27] op_sel_hi:[1,0]
	s_mov_b64 s[38:39], 0x19300000

; __device__ __forceinline__ u32x4 pack8(const f32x4 a, const f32x4 b) { u32x4 w; w.x = cvt_pk_bf16(a[0], a[1]); w.y = cvt_pk_bf16(a[2], a[3]); w.z = cvt_pk_bf16(b[0], b[1]); w.w = cvt_pk_bf16(b[2], b[3]); return w; }
; __device__ __forceinline__ void rope8(const float* tab64, int row, int fq, const f32x4 x1a, const f32x4 x2a, const f32x4 x1b, const f32x4 x2b, f32x4& a1, f32x4& a2, f32x4& b1, f32x4& b2) {
;     const float* tp = tab64 + ((size_t)pos_index_(row) * 32 + 8 * fq) * 2;
;     const f32x4 c0 = *(const f32x4*)tp, c1 = *(const f32x4*)(tp + 4), c2 = *(const f32x4*)(tp + 8), c3 = *(const f32x4*)(tp + 12);
;     rope4(x1a, x2a, c0, c1, a1, a2); rope4(x1b, x2b, c2, c3, b1, b2);
;     __device__ __forceinline__ void operator()(const f32x4 (&acc)[2][2][4][2], const Unit& u, int wr, int wc, int fr, int fq) const {
;     ...
;             for (int m = 0; m < 4; ++m) {
;                 const int rowb = u.pm * BM + ai * HALF + wr * 64 + m * 16, row0 = rowb + (fr & 7); const size_t ro0 = (size_t)row0 * 2048;
;                 float* f0 = row0 < 8192 ? (type == 1 ? okp : ovp) + ro0 : (type == 1 ? oks : ovs) + (ro0 - (size_t)8192 * 2048);
;                 if (type < 2) {
;                     f32x4 a1, a2, b1, b2; rope8(tab64, rowb + fr, fq, acc[ai][0][m][0], acc[ai][1][m][0], acc[ai][0][m][1], acc[ai][1][m][1], a1, a2, b1, b2);
;                     if (type == 0) { a1 = a1 * qscale; a2 = a2 * qscale; b1 = b1 * qscale; b2 = b2 * qscale; }
;                     st2_bf16((type == 0 ? QA : KA) + ro0 + cw + (lo ? 0 : 32), 8 * 2048, pack8(a1, b1), pack8(a2, b2), lo, dry);
;                     if (type == 1) { st2_f32<true>(f0 + cw + (lo ? 0 : 4), 8 * 2048, a1, b1, lo, dry); st2_f32<true>(f0 + cw + 32 + (lo ? 0 : 4), 8 * 2048, a2, b2, lo, dry); }
.Lrope_j_p18_7:
	v_mov_b64_e32 v[24:25], v[236:237]
	v_mov_b64_e32 v[26:27], v[238:239]
	v_mov_b64_e32 v[28:29], v[240:241]
	v_mov_b64_e32 v[30:31], v[242:243]
	v_mov_b64_e32 v[32:33], v[244:245]
	v_mov_b64_e32 v[34:35], v[246:247]
	v_mov_b64_e32 v[36:37], v[248:249]
	v_mov_b64_e32 v[38:39], v[250:251]
	s_and_b64 vcc, exec, s[6:7]
	s_mov_b64 s[6:7], 0x1b500000
	v_mov_b32_e32 v18, v24
	v_mul_f32_e32 v24, v16, v28
	v_mul_f32_e32 v40, v8, v29
	v_mul_f32_e32 v28, v8, v28
	v_mul_f32_e32 v42, v16, v29
	v_mov_b32_e32 v8, v17
	v_mov_b32_e32 v16, v9
	v_mov_b32_e32 v44, v32
	v_mul_f32_e32 v32, v12, v36
	v_mul_f32_e32 v46, v4, v37
	v_mul_f32_e32 v36, v4, v36
	v_mul_f32_e32 v48, v12, v37
	v_mov_b32_e32 v4, v13
	v_mov_b32_e32 v12, v5
	v_mov_b32_e32 v19, v26
	v_mov_b32_e32 v26, v25
	v_mov_b32_e32 v45, v34
	v_mov_b32_e32 v34, v33
	v_pk_mul_f32 v[8:9], v[8:9], v[30:31]
	v_pk_mul_f32 v[16:17], v[16:17], v[30:31]
	v_pk_mul_f32 v[52:53], v[4:5], v[38:39]
	v_pk_mul_f32 v[38:39], v[12:13], v[38:39]
	v_pk_mul_f32 v[50:51], v[6:7], v[26:27]
	v_pk_mul_f32 v[26:27], v[14:15], v[26:27]
	v_pk_mul_f32 v[30:31], v[2:3], v[34:35]
	v_pk_mul_f32 v[34:35], v[10:11], v[34:35]
	v_mov_b32_e32 v25, v8
	v_mov_b32_e32 v41, v9
	v_mov_b32_e32 v29, v16
	v_mov_b32_e32 v43, v17
	v_mov_b32_e32 v33, v52
	v_mov_b32_e32 v47, v53
	v_mov_b32_e32 v37, v38
	v_mov_b32_e32 v49, v39
	v_pk_fma_f32 v[12:13], v[14:15], v[18:19], v[50:51] neg_lo:[0,0,1] neg_hi:[0,0,1]
	v_pk_fma_f32 v[4:5], v[6:7], v[18:19], v[26:27]
	v_pk_fma_f32 v[16:17], v[10:11], v[44:45], v[30:31] neg_lo:[0,0,1] neg_hi:[0,0,1]
	v_pk_fma_f32 v[8:9], v[2:3], v[44:45], v[34:35]
	v_pk_add_f32 v[14:15], v[24:25], v[40:41] neg_lo:[0,1] neg_hi:[0,1]
	v_pk_add_f32 v[6:7], v[28:29], v[42:43]
	v_pk_add_f32 v[18:19], v[32:33], v[46:47] neg_lo:[0,1] neg_hi:[0,1]
	v_pk_add_f32 v[10:11], v[36:37], v[48:49]
	s_cbranch_vccnz .LBB0_3208
	v_pk_mul_f32 v[14:15], v[14:15], s[26:27] op_sel_hi:[1,0]
	v_pk_mul_f32 v[12:13], v[12:13], s[26:27] op_sel_hi:[1,0]
	v_pk_mul_f32 v[6:7], v[6:7], s[26:27] op_sel_hi:[1,0]
	v_pk_mul_f32 v[4:5], v[4:5], s[26:27] op_sel_hi:[1,0]
	v_pk_mul_f32 v[18:19], v[18:19], s[26:27] op_sel_hi:[1,0]
	v_pk_mul_f32 v[16:17], v[16:17], s[26:27] op_sel_hi:[1,0]
	v_pk_mul_f32 v[10:11], v[10:11], s[26:27] op_sel_hi:[1,0]
	v_pk_mul_f32 v[8:9], v[8:9], s[26:27] op_sel_hi:[1,0]
	s_mov_b64 s[6:7], 0x19300000
